# v011 + nt on GEMM3 epilogue x loads
# speedup vs baseline: 1.0046x; 1.0046x over previous
; __device__ __forceinline__ unsigned pk2(float lo, float hi) { return __builtin_bit_cast(unsigned, __builtin_convertvector((f32x2){lo, hi}, bf16x2_t)); }
;     __device__ __forceinline__ void operator()(f32x4 (&acc)[2][2][4][2], const pg8::Unit& u, int wr, int wc, int fr, int fq) const {
;         asm volatile("" : "+v"(fr), "+v"(fq));
;         const int row0 = u.pm * 256 + wr * 64 + fr, col0 = u.pn * 256 + wc * 32 + 8 * fq;
; #pragma unroll
;         for (int ai = 0; ai < 2; ++ai)
; #pragma unroll
;             for (int m = 0; m < 4; ++m) {
;                 const int row = row0 + ai * 128 + m * 16;
;                 const size_t off = (size_t)row * DM + col0;
;                 float ss = 0.f;
; #pragma unroll
;                 for (int bj = 0; bj < 2; ++bj) {
;                     const f32x4 y0 = *(const f32x4*)(x + off + bj * 128) + acc[ai][bj][m][0], y1 = *(const f32x4*)(x + off + bj * 128 + 4) + acc[ai][bj][m][1];
;                     ss += (y0[0] * y0[0] + y0[1] * y0[1]) + (y0[2] * y0[2] + y0[3] * y0[3]) + (y1[0] * y1[0] + y1[1] * y1[1]) + (y1[2] * y1[2] + y1[3] * y1[3]);
;                     *(u32x4*)(Y + (size_t)row * LDP + col0 + bj * 128) = (u32x4){pk2(y0[0], y0[1]), pk2(y0[2], y0[3]), pk2(y1[0], y1[1]), pk2(y1[2], y1[3])};
;                 }
;                 ss += __shfl_xor(ss, 16); ss += __shfl_xor(ss, 32);
;                 if (fq == 0) rsq[(size_t)row * 64 + u.pn * 4 + wc] = ss;
;             }
;     }
.LBB0_540:
	s_lshl_b32 s43, s50, 8
	v_mov_b32_e32 v134, v138
	v_mov_b32_e32 v145, v139
	s_add_i32 s43, s43, s61
	v_mov_b64_e32 v[246:247], s[16:17]
	v_add_u32_e32 v136, s43, v134
	s_lshl_b32 s43, s14, 8
	s_or_b32 s43, s43, s62
	v_ashrrev_i32_e32 v137, 31, v136
	v_lshl_add_u32 v134, v145, 3, s43
	v_lshlrev_b64 v[244:245], 14, v[136:137]
	v_ashrrev_i32_e32 v135, 31, v134
	v_lshl_add_u64 v[244:245], s[36:37], 0, v[244:245]
	v_lshl_add_u64 v[244:245], v[134:135], 2, v[244:245]
	v_mad_i64_i32 v[246:247], s[50:51], v136, s67, v[246:247]
	v_lshl_add_u64 v[246:247], v[134:135], 1, v[246:247]
	s_lshl_b32 s50, s14, 2
	s_ashr_i32 s51, s50, 31
	v_lshlrev_b64 v[248:249], 8, v[136:137]
	v_lshl_add_u64 v[248:249], s[18:19], 0, v[248:249]
	v_lshl_add_u64 v[248:249], s[50:51], 2, v[248:249]
	s_lshl_b32 s14, s60, 2
	v_lshl_add_u64 v[248:249], v[248:249], 0, s[14:15]
	s_mov_b32 s51, 0
	global_load_dwordx4 v[146:149], v[244:245], off nt
	global_load_dwordx4 v[150:153], v[244:245], off offset:16 nt
	global_load_dwordx4 v[154:157], v[244:245], off offset:512 nt
	global_load_dwordx4 v[158:161], v[244:245], off offset:528 nt
	s_mov_b32 s14, 0x40000
	v_lshl_add_u64 v[244:245], v[244:245], 0, s[14:15]
	global_load_dwordx4 v[162:165], v[244:245], off nt
	global_load_dwordx4 v[166:169], v[244:245], off offset:16 nt
	global_load_dwordx4 v[170:173], v[244:245], off offset:512 nt
	global_load_dwordx4 v[174:177], v[244:245], off offset:528 nt
	s_mov_b32 s14, 0x40000
	v_lshl_add_u64 v[244:245], v[244:245], 0, s[14:15]
	global_load_dwordx4 v[178:181], v[244:245], off nt
	global_load_dwordx4 v[182:185], v[244:245], off offset:16 nt
	global_load_dwordx4 v[186:189], v[244:245], off offset:512 nt
	global_load_dwordx4 v[190:193], v[244:245], off offset:528 nt
	s_mov_b32 s14, 0x40000
	v_lshl_add_u64 v[244:245], v[244:245], 0, s[14:15]
	global_load_dwordx4 v[194:197], v[244:245], off nt
	global_load_dwordx4 v[198:201], v[244:245], off offset:16 nt
	global_load_dwordx4 v[202:205], v[244:245], off offset:512 nt
	global_load_dwordx4 v[206:209], v[244:245], off offset:528 nt
	s_mov_b32 s14, 0x140000
	v_lshl_add_u64 v[244:245], v[244:245], 0, s[14:15]
	global_load_dwordx4 v[212:215], v[244:245], off nt
	global_load_dwordx4 v[216:219], v[244:245], off offset:16 nt
	global_load_dwordx4 v[220:223], v[244:245], off offset:512 nt
	global_load_dwordx4 v[224:227], v[244:245], off offset:528 nt
	s_mov_b32 s14, 0x40000
	v_lshl_add_u64 v[244:245], v[244:245], 0, s[14:15]
	v_and_b32_e32 v236, 64, v144
	v_xor_b32_e32 v250, 16, v144
	v_add_u32_e32 v236, 64, v236
	v_xor_b32_e32 v251, 32, v144
	v_cmp_lt_i32_e32 vcc, v250, v236
	s_nop 1
	v_cndmask_b32_e32 v250, v144, v250, vcc
	v_cmp_lt_i32_e32 vcc, v251, v236
	v_lshlrev_b32_e32 v250, 2, v250
	s_nop 0
	v_cndmask_b32_e32 v251, v144, v251, vcc
	v_lshlrev_b32_e32 v251, 2, v251
	s_waitcnt vmcnt(16)
	v_pk_add_f32 v[124:125], v[124:125], v[146:147]
	v_pk_add_f32 v[126:127], v[126:127], v[148:149]
	v_pk_add_f32 v[120:121], v[120:121], v[150:151]
	v_pk_add_f32 v[122:123], v[122:123], v[152:153]
	v_pk_add_f32 v[116:117], v[116:117], v[154:155]
	v_pk_add_f32 v[118:119], v[118:119], v[156:157]
	v_pk_add_f32 v[112:113], v[112:113], v[158:159]
	v_pk_add_f32 v[114:115], v[114:115], v[160:161]
	global_load_dwordx4 v[146:149], v[244:245], off nt
	global_load_dwordx4 v[150:153], v[244:245], off offset:16 nt
	global_load_dwordx4 v[154:157], v[244:245], off offset:512 nt
	global_load_dwordx4 v[158:161], v[244:245], off offset:528 nt
	s_mov_b32 s14, 0x40000
	v_lshl_add_u64 v[244:245], v[244:245], 0, s[14:15]
	v_cvt_pk_bf16_f32 v228, v124, v125
	v_cvt_pk_bf16_f32 v229, v126, v127
	v_cvt_pk_bf16_f32 v230, v120, v121
	v_cvt_pk_bf16_f32 v231, v122, v123
	v_cvt_pk_bf16_f32 v232, v116, v117
	v_cvt_pk_bf16_f32 v233, v118, v119
	v_cvt_pk_bf16_f32 v234, v112, v113
	v_cvt_pk_bf16_f32 v235, v114, v115
	global_store_dwordx4 v[246:247], v[228:231], off
	global_store_dwordx4 v[246:247], v[232:235], off offset:256
	s_mov_b32 s50, 0x20800
	v_lshl_add_u64 v[246:247], v[246:247], 0, s[50:51]
	v_mul_f32_e32 v236, v125, v125
	v_mul_f32_e32 v237, v127, v127
	v_mul_f32_e32 v238, v121, v121
	v_mul_f32_e32 v239, v123, v123
	v_fmac_f32_e32 v236, v124, v124
	v_fmac_f32_e32 v237, v126, v126
	v_fmac_f32_e32 v238, v120, v120
	v_fmac_f32_e32 v239, v122, v122
	v_add_f32_e32 v236, v236, v237
	v_add_f32_e32 v236, v236, v238
	v_add_f32_e32 v236, v239, v236
	v_mul_f32_e32 v240, v117, v117
	v_mul_f32_e32 v241, v119, v119
	v_mul_f32_e32 v242, v113, v113
	v_mul_f32_e32 v243, v115, v115
	v_fmac_f32_e32 v240, v116, v116
	v_fmac_f32_e32 v241, v118, v118
	v_fmac_f32_e32 v242, v112, v112
	v_fmac_f32_e32 v243, v114, v114
	v_add_f32_e32 v240, v240, v241
	v_add_f32_e32 v240, v240, v242
	v_add_f32_e32 v240, v243, v240
	v_add_f32_e32 v112, v236, v240
	s_waitcnt vmcnt(18)
; __device__ __forceinline__ unsigned pk2(float lo, float hi) { return __builtin_bit_cast(unsigned, __builtin_convertvector((f32x2){lo, hi}, bf16x2_t)); }
;     __device__ __forceinline__ void operator()(f32x4 (&acc)[2][2][4][2], const pg8::Unit& u, int wr, int wc, int fr, int fq) const {
;     ...
;                 for (int bj = 0; bj < 2; ++bj) {
;                     const f32x4 y0 = *(const f32x4*)(x + off + bj * 128) + acc[ai][bj][m][0], y1 = *(const f32x4*)(x + off + bj * 128 + 4) + acc[ai][bj][m][1];
;                     ss += (y0[0] * y0[0] + y0[1] * y0[1]) + (y0[2] * y0[2] + y0[3] * y0[3]) + (y1[0] * y1[0] + y1[1] * y1[1]) + (y1[2] * y1[2] + y1[3] * y1[3]);
;                     *(u32x4*)(Y + (size_t)row * LDP + col0 + bj * 128) = (u32x4){pk2(y0[0], y0[1]), pk2(y0[2], y0[3]), pk2(y1[0], y1[1]), pk2(y1[2], y1[3])};
;                 }
	v_pk_add_f32 v[108:109], v[108:109], v[162:163]
	v_pk_add_f32 v[110:111], v[110:111], v[164:165]
	v_pk_add_f32 v[104:105], v[104:105], v[166:167]
	v_pk_add_f32 v[106:107], v[106:107], v[168:169]
	v_pk_add_f32 v[100:101], v[100:101], v[170:171]
	v_pk_add_f32 v[102:103], v[102:103], v[172:173]
	v_pk_add_f32 v[96:97], v[96:97], v[174:175]
	v_pk_add_f32 v[98:99], v[98:99], v[176:177]
	global_load_dwordx4 v[162:165], v[244:245], off nt
	global_load_dwordx4 v[166:169], v[244:245], off offset:16 nt
	global_load_dwordx4 v[170:173], v[244:245], off offset:512 nt
	global_load_dwordx4 v[174:177], v[244:245], off offset:528 nt
	s_mov_b32 s14, 0x40000
	v_lshl_add_u64 v[244:245], v[244:245], 0, s[14:15]
	v_cvt_pk_bf16_f32 v228, v108, v109
	v_cvt_pk_bf16_f32 v229, v110, v111
	v_cvt_pk_bf16_f32 v230, v104, v105
	v_cvt_pk_bf16_f32 v231, v106, v107
	v_cvt_pk_bf16_f32 v232, v100, v101
	v_cvt_pk_bf16_f32 v233, v102, v103
	v_cvt_pk_bf16_f32 v234, v96, v97
	v_cvt_pk_bf16_f32 v235, v98, v99
	global_store_dwordx4 v[246:247], v[228:231], off
	global_store_dwordx4 v[246:247], v[232:235], off offset:256
	s_mov_b32 s50, 0x20800
	v_lshl_add_u64 v[246:247], v[246:247], 0, s[50:51]
	v_mul_f32_e32 v236, v109, v109
	v_mul_f32_e32 v237, v111, v111
	v_mul_f32_e32 v238, v105, v105
	v_mul_f32_e32 v239, v107, v107
	v_fmac_f32_e32 v236, v108, v108
	v_fmac_f32_e32 v237, v110, v110
	v_fmac_f32_e32 v238, v104, v104
	v_fmac_f32_e32 v239, v106, v106
	v_add_f32_e32 v236, v236, v237
	v_add_f32_e32 v236, v236, v238
	v_add_f32_e32 v236, v239, v236
	v_mul_f32_e32 v240, v101, v101
	v_mul_f32_e32 v241, v103, v103
	v_mul_f32_e32 v242, v97, v97
	v_mul_f32_e32 v243, v99, v99
	v_fmac_f32_e32 v240, v100, v100
	v_fmac_f32_e32 v241, v102, v102
	v_fmac_f32_e32 v242, v96, v96
	v_fmac_f32_e32 v243, v98, v98
	v_add_f32_e32 v240, v240, v241
	v_add_f32_e32 v240, v240, v242
	v_add_f32_e32 v240, v243, v240
	v_add_f32_e32 v113, v236, v240
	s_waitcnt vmcnt(20)
	v_pk_add_f32 v[92:93], v[92:93], v[178:179]
	v_pk_add_f32 v[94:95], v[94:95], v[180:181]
	v_pk_add_f32 v[88:89], v[88:89], v[182:183]
	v_pk_add_f32 v[90:91], v[90:91], v[184:185]
	v_pk_add_f32 v[84:85], v[84:85], v[186:187]
	v_pk_add_f32 v[86:87], v[86:87], v[188:189]
	v_pk_add_f32 v[80:81], v[80:81], v[190:191]
	v_pk_add_f32 v[82:83], v[82:83], v[192:193]
	global_load_dwordx4 v[178:181], v[244:245], off nt
	global_load_dwordx4 v[182:185], v[244:245], off offset:16 nt
	global_load_dwordx4 v[186:189], v[244:245], off offset:512 nt
	global_load_dwordx4 v[190:193], v[244:245], off offset:528 nt
	v_cvt_pk_bf16_f32 v228, v92, v93
	v_cvt_pk_bf16_f32 v229, v94, v95
	v_cvt_pk_bf16_f32 v230, v88, v89
	v_cvt_pk_bf16_f32 v231, v90, v91
	v_cvt_pk_bf16_f32 v232, v84, v85
	v_cvt_pk_bf16_f32 v233, v86, v87
	v_cvt_pk_bf16_f32 v234, v80, v81
	v_cvt_pk_bf16_f32 v235, v82, v83
	global_store_dwordx4 v[246:247], v[228:231], off
	global_store_dwordx4 v[246:247], v[232:235], off offset:256
	s_mov_b32 s50, 0x20800
	v_lshl_add_u64 v[246:247], v[246:247], 0, s[50:51]
	v_mul_f32_e32 v236, v93, v93
	v_mul_f32_e32 v237, v95, v95
	v_mul_f32_e32 v238, v89, v89
	v_mul_f32_e32 v239, v91, v91
	v_fmac_f32_e32 v236, v92, v92
	v_fmac_f32_e32 v237, v94, v94
	v_fmac_f32_e32 v238, v88, v88
	v_fmac_f32_e32 v239, v90, v90
	v_add_f32_e32 v236, v236, v237
	v_add_f32_e32 v236, v236, v238
	v_add_f32_e32 v236, v239, v236
	v_mul_f32_e32 v240, v85, v85
	v_mul_f32_e32 v241, v87, v87
	v_mul_f32_e32 v242, v81, v81
	v_mul_f32_e32 v243, v83, v83
	v_fmac_f32_e32 v240, v84, v84
	v_fmac_f32_e32 v241, v86, v86
	v_fmac_f32_e32 v242, v80, v80
	v_fmac_f32_e32 v243, v82, v82
	v_add_f32_e32 v240, v240, v241
	v_add_f32_e32 v240, v240, v242
	v_add_f32_e32 v240, v243, v240
	v_add_f32_e32 v114, v236, v240
	s_waitcnt vmcnt(22)
	v_pk_add_f32 v[76:77], v[76:77], v[194:195]
	v_pk_add_f32 v[78:79], v[78:79], v[196:197]
	v_pk_add_f32 v[72:73], v[72:73], v[198:199]
	v_pk_add_f32 v[74:75], v[74:75], v[200:201]
	v_pk_add_f32 v[68:69], v[68:69], v[202:203]
	v_pk_add_f32 v[70:71], v[70:71], v[204:205]
	v_pk_add_f32 v[64:65], v[64:65], v[206:207]
	v_pk_add_f32 v[66:67], v[66:67], v[208:209]
	v_cvt_pk_bf16_f32 v228, v76, v77
	v_cvt_pk_bf16_f32 v229, v78, v79
	v_cvt_pk_bf16_f32 v230, v72, v73
	v_cvt_pk_bf16_f32 v231, v74, v75
	v_cvt_pk_bf16_f32 v232, v68, v69
	v_cvt_pk_bf16_f32 v233, v70, v71
	v_cvt_pk_bf16_f32 v234, v64, v65
	v_cvt_pk_bf16_f32 v235, v66, v67
	global_store_dwordx4 v[246:247], v[228:231], off
	global_store_dwordx4 v[246:247], v[232:235], off offset:256
	s_mov_b32 s50, 0xa2800
	v_lshl_add_u64 v[246:247], v[246:247], 0, s[50:51]
	v_mul_f32_e32 v236, v77, v77
	v_mul_f32_e32 v237, v79, v79
	v_mul_f32_e32 v238, v73, v73
	v_mul_f32_e32 v239, v75, v75
	v_fmac_f32_e32 v236, v76, v76
	v_fmac_f32_e32 v237, v78, v78
	v_fmac_f32_e32 v238, v72, v72
	v_fmac_f32_e32 v239, v74, v74
	v_add_f32_e32 v236, v236, v237
	v_add_f32_e32 v236, v236, v238
	v_add_f32_e32 v236, v239, v236
	v_mul_f32_e32 v240, v69, v69
	v_mul_f32_e32 v241, v71, v71
	v_mul_f32_e32 v242, v65, v65
	v_mul_f32_e32 v243, v67, v67
	v_fmac_f32_e32 v240, v68, v68
	v_fmac_f32_e32 v241, v70, v70
	v_fmac_f32_e32 v242, v64, v64
	v_fmac_f32_e32 v243, v66, v66
	v_add_f32_e32 v240, v240, v241
	v_add_f32_e32 v240, v240, v242
	v_add_f32_e32 v240, v243, v240
	v_add_f32_e32 v115, v236, v240
	s_waitcnt vmcnt(20)
; __device__ __forceinline__ unsigned pk2(float lo, float hi) { return __builtin_bit_cast(unsigned, __builtin_convertvector((f32x2){lo, hi}, bf16x2_t)); }
;     __device__ __forceinline__ void operator()(f32x4 (&acc)[2][2][4][2], const pg8::Unit& u, int wr, int wc, int fr, int fq) const {
;     ...
;                 for (int bj = 0; bj < 2; ++bj) {
;                     const f32x4 y0 = *(const f32x4*)(x + off + bj * 128) + acc[ai][bj][m][0], y1 = *(const f32x4*)(x + off + bj * 128 + 4) + acc[ai][bj][m][1];
;                     ss += (y0[0] * y0[0] + y0[1] * y0[1]) + (y0[2] * y0[2] + y0[3] * y0[3]) + (y1[0] * y1[0] + y1[1] * y1[1]) + (y1[2] * y1[2] + y1[3] * y1[3]);
;                     *(u32x4*)(Y + (size_t)row * LDP + col0 + bj * 128) = (u32x4){pk2(y0[0], y0[1]), pk2(y0[2], y0[3]), pk2(y1[0], y1[1]), pk2(y1[2], y1[3])};
;                 }
	v_pk_add_f32 v[60:61], v[60:61], v[212:213]
	v_pk_add_f32 v[62:63], v[62:63], v[214:215]
	v_pk_add_f32 v[56:57], v[56:57], v[216:217]
	v_pk_add_f32 v[58:59], v[58:59], v[218:219]
	v_pk_add_f32 v[52:53], v[52:53], v[220:221]
	v_pk_add_f32 v[54:55], v[54:55], v[222:223]
	v_pk_add_f32 v[48:49], v[48:49], v[224:225]
	v_pk_add_f32 v[50:51], v[50:51], v[226:227]
	v_cvt_pk_bf16_f32 v228, v60, v61
	v_cvt_pk_bf16_f32 v229, v62, v63
	v_cvt_pk_bf16_f32 v230, v56, v57
	v_cvt_pk_bf16_f32 v231, v58, v59
	v_cvt_pk_bf16_f32 v232, v52, v53
	v_cvt_pk_bf16_f32 v233, v54, v55
	v_cvt_pk_bf16_f32 v234, v48, v49
	v_cvt_pk_bf16_f32 v235, v50, v51
	global_store_dwordx4 v[246:247], v[228:231], off
	global_store_dwordx4 v[246:247], v[232:235], off offset:256
	s_mov_b32 s50, 0x20800
	v_lshl_add_u64 v[246:247], v[246:247], 0, s[50:51]
	v_mul_f32_e32 v236, v61, v61
	v_mul_f32_e32 v237, v63, v63
	v_mul_f32_e32 v238, v57, v57
	v_mul_f32_e32 v239, v59, v59
	v_fmac_f32_e32 v236, v60, v60
	v_fmac_f32_e32 v237, v62, v62
	v_fmac_f32_e32 v238, v56, v56
	v_fmac_f32_e32 v239, v58, v58
	v_add_f32_e32 v236, v236, v237
	v_add_f32_e32 v236, v236, v238
	v_add_f32_e32 v236, v239, v236
	v_mul_f32_e32 v240, v53, v53
	v_mul_f32_e32 v241, v55, v55
	v_mul_f32_e32 v242, v49, v49
	v_mul_f32_e32 v243, v51, v51
	v_fmac_f32_e32 v240, v52, v52
	v_fmac_f32_e32 v241, v54, v54
	v_fmac_f32_e32 v242, v48, v48
	v_fmac_f32_e32 v243, v50, v50
	v_add_f32_e32 v240, v240, v241
	v_add_f32_e32 v240, v240, v242
	v_add_f32_e32 v240, v243, v240
	v_add_f32_e32 v116, v236, v240
	s_waitcnt vmcnt(18)
	v_pk_add_f32 v[44:45], v[44:45], v[146:147]
	v_pk_add_f32 v[46:47], v[46:47], v[148:149]
	v_pk_add_f32 v[40:41], v[40:41], v[150:151]
	v_pk_add_f32 v[42:43], v[42:43], v[152:153]
	v_pk_add_f32 v[36:37], v[36:37], v[154:155]
	v_pk_add_f32 v[38:39], v[38:39], v[156:157]
	v_pk_add_f32 v[32:33], v[32:33], v[158:159]
	v_pk_add_f32 v[34:35], v[34:35], v[160:161]
	v_cvt_pk_bf16_f32 v228, v44, v45
	v_cvt_pk_bf16_f32 v229, v46, v47
	v_cvt_pk_bf16_f32 v230, v40, v41
	v_cvt_pk_bf16_f32 v231, v42, v43
	v_cvt_pk_bf16_f32 v232, v36, v37
	v_cvt_pk_bf16_f32 v233, v38, v39
	v_cvt_pk_bf16_f32 v234, v32, v33
	v_cvt_pk_bf16_f32 v235, v34, v35
	global_store_dwordx4 v[246:247], v[228:231], off
	global_store_dwordx4 v[246:247], v[232:235], off offset:256
	s_mov_b32 s50, 0x20800
	v_lshl_add_u64 v[246:247], v[246:247], 0, s[50:51]
	v_mul_f32_e32 v236, v45, v45
	v_mul_f32_e32 v237, v47, v47
	v_mul_f32_e32 v238, v41, v41
	v_mul_f32_e32 v239, v43, v43
	v_fmac_f32_e32 v236, v44, v44
	v_fmac_f32_e32 v237, v46, v46
	v_fmac_f32_e32 v238, v40, v40
	v_fmac_f32_e32 v239, v42, v42
	v_add_f32_e32 v236, v236, v237
	v_add_f32_e32 v236, v236, v238
	v_add_f32_e32 v236, v239, v236
	v_mul_f32_e32 v240, v37, v37
	v_mul_f32_e32 v241, v39, v39
	v_mul_f32_e32 v242, v33, v33
	v_mul_f32_e32 v243, v35, v35
	v_fmac_f32_e32 v240, v36, v36
	v_fmac_f32_e32 v241, v38, v38
	v_fmac_f32_e32 v242, v32, v32
	v_fmac_f32_e32 v243, v34, v34
	v_add_f32_e32 v240, v240, v241
	v_add_f32_e32 v240, v240, v242
	v_add_f32_e32 v240, v243, v240
	v_add_f32_e32 v117, v236, v240
	s_waitcnt vmcnt(14)
	v_pk_add_f32 v[28:29], v[28:29], v[162:163]
	v_pk_add_f32 v[30:31], v[30:31], v[164:165]
	v_pk_add_f32 v[24:25], v[24:25], v[166:167]
	v_pk_add_f32 v[26:27], v[26:27], v[168:169]
	v_pk_add_f32 v[20:21], v[20:21], v[170:171]
	v_pk_add_f32 v[22:23], v[22:23], v[172:173]
	v_pk_add_f32 v[16:17], v[16:17], v[174:175]
	v_pk_add_f32 v[18:19], v[18:19], v[176:177]
	v_cvt_pk_bf16_f32 v228, v28, v29
	v_cvt_pk_bf16_f32 v229, v30, v31
	v_cvt_pk_bf16_f32 v230, v24, v25
	v_cvt_pk_bf16_f32 v231, v26, v27
	v_cvt_pk_bf16_f32 v232, v20, v21
	v_cvt_pk_bf16_f32 v233, v22, v23
	v_cvt_pk_bf16_f32 v234, v16, v17
	v_cvt_pk_bf16_f32 v235, v18, v19
	global_store_dwordx4 v[246:247], v[228:231], off
	global_store_dwordx4 v[246:247], v[232:235], off offset:256
	s_mov_b32 s50, 0x20800
	v_lshl_add_u64 v[246:247], v[246:247], 0, s[50:51]
	v_mul_f32_e32 v236, v29, v29
	v_mul_f32_e32 v237, v31, v31
	v_mul_f32_e32 v238, v25, v25
	v_mul_f32_e32 v239, v27, v27
	v_fmac_f32_e32 v236, v28, v28
	v_fmac_f32_e32 v237, v30, v30
	v_fmac_f32_e32 v238, v24, v24
	v_fmac_f32_e32 v239, v26, v26
	v_add_f32_e32 v236, v236, v237
	v_add_f32_e32 v236, v236, v238
	v_add_f32_e32 v236, v239, v236
	v_mul_f32_e32 v240, v21, v21
	v_mul_f32_e32 v241, v23, v23
	v_mul_f32_e32 v242, v17, v17
	v_mul_f32_e32 v243, v19, v19
	v_fmac_f32_e32 v240, v20, v20
	v_fmac_f32_e32 v241, v22, v22
	v_fmac_f32_e32 v242, v16, v16
	v_fmac_f32_e32 v243, v18, v18
	v_add_f32_e32 v240, v240, v241
	v_add_f32_e32 v240, v240, v242
	v_add_f32_e32 v240, v243, v240
	v_add_f32_e32 v118, v236, v240
	s_waitcnt vmcnt(10)
; __device__ __forceinline__ unsigned pk2(float lo, float hi) { return __builtin_bit_cast(unsigned, __builtin_convertvector((f32x2){lo, hi}, bf16x2_t)); }
;     __device__ __forceinline__ void operator()(f32x4 (&acc)[2][2][4][2], const pg8::Unit& u, int wr, int wc, int fr, int fq) const {
;     ...
;                     const f32x4 y0 = *(const f32x4*)(x + off + bj * 128) + acc[ai][bj][m][0], y1 = *(const f32x4*)(x + off + bj * 128 + 4) + acc[ai][bj][m][1];
;                     ss += (y0[0] * y0[0] + y0[1] * y0[1]) + (y0[2] * y0[2] + y0[3] * y0[3]) + (y1[0] * y1[0] + y1[1] * y1[1]) + (y1[2] * y1[2] + y1[3] * y1[3]);
;                     *(u32x4*)(Y + (size_t)row * LDP + col0 + bj * 128) = (u32x4){pk2(y0[0], y0[1]), pk2(y0[2], y0[3]), pk2(y1[0], y1[1]), pk2(y1[2], y1[3])};
;                 }
;                 ss += __shfl_xor(ss, 16); ss += __shfl_xor(ss, 32);
;                 if (fq == 0) rsq[(size_t)row * 64 + u.pn * 4 + wc] = ss;
;             }
;     }
	v_pk_add_f32 v[12:13], v[12:13], v[178:179]
	v_pk_add_f32 v[14:15], v[14:15], v[180:181]
	v_pk_add_f32 v[8:9], v[8:9], v[182:183]
	v_pk_add_f32 v[10:11], v[10:11], v[184:185]
	v_pk_add_f32 v[4:5], v[4:5], v[186:187]
	v_pk_add_f32 v[6:7], v[6:7], v[188:189]
	v_pk_add_f32 v[0:1], v[0:1], v[190:191]
	v_pk_add_f32 v[2:3], v[2:3], v[192:193]
	v_cvt_pk_bf16_f32 v228, v12, v13
	v_cvt_pk_bf16_f32 v229, v14, v15
	v_cvt_pk_bf16_f32 v230, v8, v9
	v_cvt_pk_bf16_f32 v231, v10, v11
	v_cvt_pk_bf16_f32 v232, v4, v5
	v_cvt_pk_bf16_f32 v233, v6, v7
	v_cvt_pk_bf16_f32 v234, v0, v1
	v_cvt_pk_bf16_f32 v235, v2, v3
	global_store_dwordx4 v[246:247], v[228:231], off
	global_store_dwordx4 v[246:247], v[232:235], off offset:256
	v_mul_f32_e32 v236, v13, v13
	v_mul_f32_e32 v237, v15, v15
	v_mul_f32_e32 v238, v9, v9
	v_mul_f32_e32 v239, v11, v11
	v_fmac_f32_e32 v236, v12, v12
	v_fmac_f32_e32 v237, v14, v14
	v_fmac_f32_e32 v238, v8, v8
	v_fmac_f32_e32 v239, v10, v10
	v_add_f32_e32 v236, v236, v237
	v_add_f32_e32 v236, v236, v238
	v_add_f32_e32 v236, v239, v236
	v_mul_f32_e32 v240, v5, v5
	v_mul_f32_e32 v241, v7, v7
	v_mul_f32_e32 v242, v1, v1
	v_mul_f32_e32 v243, v3, v3
	v_fmac_f32_e32 v240, v4, v4
	v_fmac_f32_e32 v241, v6, v6
	v_fmac_f32_e32 v242, v0, v0
	v_fmac_f32_e32 v243, v2, v2
	v_add_f32_e32 v240, v240, v241
	v_add_f32_e32 v240, v240, v242
	v_add_f32_e32 v240, v243, v240
	v_add_f32_e32 v119, v236, v240
	ds_bpermute_b32 v236, v250, v112
	ds_bpermute_b32 v237, v250, v113
	ds_bpermute_b32 v238, v250, v114
	ds_bpermute_b32 v239, v250, v115
	ds_bpermute_b32 v240, v250, v116
	ds_bpermute_b32 v241, v250, v117
	ds_bpermute_b32 v242, v250, v118
	ds_bpermute_b32 v243, v250, v119
	v_cmp_eq_u32_e32 vcc, 0, v145
	s_waitcnt lgkmcnt(0)
	v_add_f32_e32 v112, v112, v236
	v_add_f32_e32 v113, v113, v237
	v_add_f32_e32 v114, v114, v238
	v_add_f32_e32 v115, v115, v239
	v_add_f32_e32 v116, v116, v240
	v_add_f32_e32 v117, v117, v241
	v_add_f32_e32 v118, v118, v242
	v_add_f32_e32 v119, v119, v243
	ds_bpermute_b32 v236, v251, v112
	ds_bpermute_b32 v237, v251, v113
	ds_bpermute_b32 v238, v251, v114
	ds_bpermute_b32 v239, v251, v115
	ds_bpermute_b32 v240, v251, v116
	ds_bpermute_b32 v241, v251, v117
	ds_bpermute_b32 v242, v251, v118
	ds_bpermute_b32 v243, v251, v119
	s_waitcnt lgkmcnt(0)
	v_add_f32_e32 v112, v112, v236
	v_add_f32_e32 v113, v113, v237
	v_add_f32_e32 v114, v114, v238
	v_add_f32_e32 v115, v115, v239
	v_add_f32_e32 v116, v116, v240
	v_add_f32_e32 v117, v117, v241
	v_add_f32_e32 v118, v118, v242
	v_add_f32_e32 v119, v119, v243
	s_and_saveexec_b64 s[52:53], vcc
	global_store_dword v[248:249], v112, off
	s_mov_b32 s50, 0x1000
	v_lshl_add_u64 v[248:249], v[248:249], 0, s[50:51]
	global_store_dword v[248:249], v113, off
	s_mov_b32 s50, 0x1000
	v_lshl_add_u64 v[248:249], v[248:249], 0, s[50:51]
	global_store_dword v[248:249], v114, off
	s_mov_b32 s50, 0x1000
	v_lshl_add_u64 v[248:249], v[248:249], 0, s[50:51]
	global_store_dword v[248:249], v115, off
	s_mov_b32 s50, 0x5000
	v_lshl_add_u64 v[248:249], v[248:249], 0, s[50:51]
	global_store_dword v[248:249], v116, off
	s_mov_b32 s50, 0x1000
	v_lshl_add_u64 v[248:249], v[248:249], 0, s[50:51]
	global_store_dword v[248:249], v117, off
	s_mov_b32 s50, 0x1000
	v_lshl_add_u64 v[248:249], v[248:249], 0, s[50:51]
	global_store_dword v[248:249], v118, off
	s_mov_b32 s50, 0x1000
	v_lshl_add_u64 v[248:249], v[248:249], 0, s[50:51]
	global_store_dword v[248:249], v119, off
	s_or_b64 exec, exec, s[52:53]
	s_andn2_b64 vcc, exec, s[0:1]
	s_mov_b64 s[0:1], -1
	s_cbranch_vccnz .LBB0_529
	s_andn2_b64 vcc, exec, s[12:13]
	s_cbranch_vccnz .LBB0_528
	s_barrier
	s_branch .LBB0_528
